# NSA window loop: batch K ds_reads before QK MFMAs and prefetch V ds_reads before PV MFMAs (counted lgkmcnt)
# speedup vs baseline: 1.0171x; 1.0058x over previous
; #define MFMA32(a, b, c) __builtin_amdgcn_mfma_f32_32x32x16_bf16((a), (b), (c), 0, 0, 0)
; DI void qk_tile(const u16* Ks, const bf16x8* qf, f32x16* s, int rl, int hh) {
; #pragma unroll
;   for (int kb = 0; kb < 2; ++kb) {
; #pragma unroll
;     for (int i = 0; i < 16; ++i) s[kb][i] = 0.f;
; #pragma unroll
;     for (int ks = 0; ks < 4; ++ks) {
;       bf16x8 a = *(const bf16x8*)(Ks + (kb * 32 + rl) * KVS + ks * 16 + hh * 8);
;       s[kb] = MFMA32(a, qf[ks], s[kb]);
;     }
;   }
; }
; template <int MODE>
; DI void osm(f32x16* s, uint32_t vm, float& m, float& l, f32x16* o) {
;   float mx = -1e30f;
; #pragma unroll
;   for (int kb = 0; kb < 2; ++kb)
; #pragma unroll
;     for (int i = 0; i < 16; ++i) {
;       if (MODE == 2) s[kb][i] = ((vm >> (kb * 16 + i)) & 1u) ? s[kb][i] : -1e30f;
;       mx = fmaxf(mx, s[kb][i]);
;     }
;   mx *= SCL2;
;   if (MODE == 1) mx = vm ? mx : -1e30f;
.LBB0_1778:
	s_or_b64 exec, exec, s[12:13]
	v_cmp_ne_u32_e64 s[10:11], 0, v128
	s_and_b32 s19, s5, 1
	s_mov_b64 vcc, s[10:11]
	s_cbranch_vccz .LBB0_1791
	s_mul_i32 s12, s19, 0x4800
	v_or_b32_e32 v202, s12, v0
	v_lshl_add_u32 v129, v246, 1, v202
	ds_read_b128 v[130:133], v129
	ds_read_b128 v[134:137], v129 offset:32
	ds_read_b128 v[138:141], v129 offset:64
	ds_read_b128 v[160:163], v129 offset:96
	ds_read_b128 v[112:115], v129 offset:4608
	ds_read_b128 v[164:167], v129 offset:4640
	ds_read_b128 v[168:171], v129 offset:4672
	ds_read_b128 v[172:175], v129 offset:4704
	v_cmp_eq_u32_e32 vcc, -1, v128
	v_cmp_eq_u32_e64 s[12:13], 0, v128
	s_cmp_lg_u64 vcc, -1
	s_waitcnt vmcnt(2) lgkmcnt(7)
	v_mfma_f32_32x32x16_bf16 v[144:159], v[130:133], v[2:5], 0
	s_waitcnt lgkmcnt(6)
	v_mfma_f32_32x32x16_bf16 v[144:159], v[134:137], v[176:179], v[144:159]
	s_waitcnt lgkmcnt(5)
	v_mfma_f32_32x32x16_bf16 v[144:159], v[138:141], v[180:183], v[144:159]
	s_waitcnt lgkmcnt(4)
	v_mfma_f32_32x32x16_bf16 v[144:159], v[160:163], v[184:187], v[144:159]
	s_waitcnt lgkmcnt(3)
	v_mfma_f32_32x32x16_bf16 v[112:127], v[112:115], v[2:5], 0
	s_waitcnt lgkmcnt(2)
	v_mfma_f32_32x32x16_bf16 v[112:127], v[164:167], v[176:179], v[112:127]
	s_waitcnt lgkmcnt(1)
	v_mfma_f32_32x32x16_bf16 v[112:127], v[168:171], v[180:183], v[112:127]
	s_waitcnt lgkmcnt(0)
	v_mfma_f32_32x32x16_bf16 v[112:127], v[172:175], v[184:187], v[112:127]
	s_cbranch_scc0 .LBB0_1792
	s_or_b64 s[12:13], s[12:13], vcc
	s_cmp_lg_u64 s[12:13], -1
	s_cbranch_scc0 .LBB0_1793
	v_and_b32_e32 v129, 1, v128
	v_cmp_eq_u32_e32 vcc, 1, v129
	v_and_b32_e32 v130, 2, v128
	v_and_b32_e32 v132, 4, v128
	v_cndmask_b32_e32 v129, v204, v144, vcc
	v_cmp_ne_u32_e32 vcc, 0, v130
	v_and_b32_e32 v133, 8, v128
	v_and_b32_e32 v134, 16, v128
	v_cndmask_b32_e32 v130, v204, v145, vcc
	v_cmp_ne_u32_e32 vcc, 0, v132
	v_and_b32_e32 v135, 32, v128
	v_and_b32_e32 v136, 64, v128
	v_cndmask_b32_e32 v132, v204, v146, vcc
	v_cmp_ne_u32_e32 vcc, 0, v133
	v_and_b32_e32 v137, 0x80, v128
	v_and_b32_e32 v138, 0x100, v128
	v_cndmask_b32_e32 v133, v204, v147, vcc
	v_cmp_ne_u32_e32 vcc, 0, v134
	v_and_b32_e32 v139, 0x200, v128
	v_and_b32_e32 v140, 0x400, v128
	v_cndmask_b32_e32 v134, v204, v148, vcc
	v_cmp_ne_u32_e32 vcc, 0, v135
	v_and_b32_e32 v141, 0x800, v128
	v_and_b32_e32 v142, 0x1000, v128
	v_cndmask_b32_e32 v135, v204, v149, vcc
	v_cmp_ne_u32_e32 vcc, 0, v136
	v_and_b32_e32 v143, 0x2000, v128
	v_and_b32_e32 v160, 0x4000, v128
	v_cndmask_b32_e32 v136, v204, v150, vcc
	v_cmp_ne_u32_e32 vcc, 0, v137
	v_and_b32_e32 v161, 0x8000, v128
	v_and_b32_e32 v162, 0x10000, v128
	v_cndmask_b32_e32 v137, v204, v151, vcc
	v_cmp_ne_u32_e32 vcc, 0, v138
	v_and_b32_e32 v163, 0x20000, v128
	v_and_b32_e32 v164, 0x40000, v128
	v_cndmask_b32_e32 v138, v204, v152, vcc
	v_cmp_ne_u32_e32 vcc, 0, v139
	v_max3_f32 v131, v129, s77, v130
	v_and_b32_e32 v165, 0x80000, v128
	v_cndmask_b32_e32 v139, v204, v153, vcc
	v_cmp_ne_u32_e32 vcc, 0, v140
	v_max3_f32 v131, v131, v132, v133
	v_and_b32_e32 v166, 0x100000, v128
	v_cndmask_b32_e32 v140, v204, v154, vcc
	v_cmp_ne_u32_e32 vcc, 0, v141
	v_max3_f32 v131, v131, v134, v135
	v_and_b32_e32 v167, 0x200000, v128
	v_cndmask_b32_e32 v141, v204, v155, vcc
	v_cmp_ne_u32_e32 vcc, 0, v142
	v_max3_f32 v131, v131, v136, v137
	v_and_b32_e32 v168, 0x400000, v128
	v_cndmask_b32_e32 v142, v204, v156, vcc
	v_cmp_ne_u32_e32 vcc, 0, v143
	v_max3_f32 v131, v131, v138, v139
	v_and_b32_e32 v169, 0x800000, v128
	v_cndmask_b32_e32 v143, v204, v157, vcc
	v_cmp_ne_u32_e32 vcc, 0, v160
	v_max3_f32 v131, v131, v140, v141
	v_and_b32_e32 v170, 0x1000000, v128
	v_cndmask_b32_e32 v160, v204, v158, vcc
	v_cmp_ne_u32_e32 vcc, 0, v161
	v_max3_f32 v131, v131, v142, v143
	v_and_b32_e32 v171, 0x2000000, v128
	v_cndmask_b32_e32 v161, v204, v159, vcc
	v_cmp_ne_u32_e32 vcc, 0, v162
	v_max3_f32 v131, v131, v160, v161
	v_and_b32_e32 v172, 0x4000000, v128
	v_cndmask_b32_e32 v162, v204, v112, vcc
	v_cmp_ne_u32_e32 vcc, 0, v163
	v_and_b32_e32 v173, 0x8000000, v128
	v_and_b32_e32 v174, 0x10000000, v128
	v_cndmask_b32_e32 v163, v204, v113, vcc
	v_cmp_ne_u32_e32 vcc, 0, v164
	v_max3_f32 v131, v131, v162, v163
	v_and_b32_e32 v175, 0x20000000, v128
	v_cndmask_b32_e32 v164, v204, v114, vcc
	v_cmp_ne_u32_e32 vcc, 0, v165
	v_and_b32_e32 v198, 2.0, v128
	s_nop 0
	v_cndmask_b32_e32 v165, v204, v115, vcc
	v_cmp_ne_u32_e32 vcc, 0, v166
	v_max3_f32 v131, v131, v164, v165
	s_nop 0
	v_cndmask_b32_e32 v166, v204, v116, vcc
	v_cmp_ne_u32_e32 vcc, 0, v167
	s_nop 1
	v_cndmask_b32_e32 v167, v204, v117, vcc
	v_cmp_ne_u32_e32 vcc, 0, v168
	v_max3_f32 v131, v131, v166, v167
	s_nop 0
	v_cndmask_b32_e32 v168, v204, v118, vcc
; DI float fexp2(float x) { return __builtin_amdgcn_exp2f(x); }
; template <int MODE>
; DI void osm(f32x16* s, uint32_t vm, float& m, float& l, f32x16* o) {
;     ...
;     for (int i = 0; i < 16; ++i) {
;       if (MODE == 2) s[kb][i] = ((vm >> (kb * 16 + i)) & 1u) ? s[kb][i] : -1e30f;
;       mx = fmaxf(mx, s[kb][i]);
;     }
;   mx *= SCL2;
;   if (MODE == 1) mx = vm ? mx : -1e30f;
;   mx = xmax32(mx);
;   const float mn = fmaxf(m, mx);
;   const float alpha = fexp2(m - mn);
;   const bool rowok = (MODE == 1) ? (vm != 0u) : true;
;   const float mu = (rowok && mn > -1e29f) ? mn : 1e30f;
;   float rs = 0.f;
; #pragma unroll
;   for (int kb = 0; kb < 2; ++kb)
; #pragma unroll
;     for (int i = 0; i < 16; ++i) {
;       const float pv = fexp2(__builtin_fmaf(s[kb][i], SCL2, -mu));
;       s[kb][i] = pv;
;       rs += pv;
;     }
;   rs = xsum32(rs);
;   l = l * alpha + rs;
;   if (__ballot(mn > m) != 0ull) {
; #pragma unroll
;     for (int db = 0; db < 2; ++db)
; #pragma unroll
;       for (int i = 0; i < 16; ++i) o[db][i] *= alpha;
;   }
;   m = mn;
	v_cmp_ne_u32_e32 vcc, 0, v169
	s_nop 1
	v_cndmask_b32_e32 v169, v204, v119, vcc
	v_cmp_ne_u32_e32 vcc, 0, v170
	v_max3_f32 v131, v131, v168, v169
	s_nop 0
	v_cndmask_b32_e32 v170, v204, v120, vcc
	v_cmp_ne_u32_e32 vcc, 0, v171
	s_nop 1
	v_cndmask_b32_e32 v171, v204, v121, vcc
	v_cmp_ne_u32_e32 vcc, 0, v172
	v_max3_f32 v131, v131, v170, v171
	s_nop 0
	v_cndmask_b32_e32 v172, v204, v122, vcc
	v_cmp_ne_u32_e32 vcc, 0, v173
	s_nop 1
	v_cndmask_b32_e32 v173, v204, v123, vcc
	v_cmp_ne_u32_e32 vcc, 0, v174
	v_max3_f32 v131, v131, v172, v173
	s_nop 0
	v_cndmask_b32_e32 v174, v204, v124, vcc
	v_cmp_ne_u32_e32 vcc, 0, v175
	s_nop 1
	v_cndmask_b32_e32 v175, v204, v125, vcc
	v_cmp_ne_u32_e32 vcc, 0, v198
	v_max3_f32 v131, v131, v174, v175
	s_nop 0
	v_cndmask_b32_e32 v198, v204, v126, vcc
	v_cmp_gt_i32_e32 vcc, 0, v128
	s_nop 1
	v_cndmask_b32_e32 v229, v204, v127, vcc
	v_max3_f32 v128, v131, v198, v229
	v_mul_f32_e32 v128, 0x3e38aa3b, v128
	v_mov_b32_e32 v131, v128
	s_nop 1
	v_permlane32_swap_b32_e32 v128, v131
	v_max3_f32 v249, v201, v128, v131
	v_cmp_lt_f32_e32 vcc, s1, v249
	v_sub_f32_e32 v250, v201, v249
	s_nop 0
	v_cndmask_b32_e64 v251, v204, -v249, vcc
	v_fmamk_f32 v128, v129, 0x3e38aa3b, v251
	v_exp_f32_e32 v128, v128
	v_fmamk_f32 v129, v130, 0x3e38aa3b, v251
	v_exp_f32_e32 v129, v129
	v_fmamk_f32 v130, v132, 0x3e38aa3b, v251
	v_exp_f32_e32 v130, v130
	v_fmamk_f32 v131, v133, 0x3e38aa3b, v251
	v_exp_f32_e32 v131, v131
	v_add_f32_e32 v132, 0, v128
	v_add_f32_e32 v132, v129, v132
	v_add_f32_e32 v132, v130, v132
	v_add_f32_e32 v252, v131, v132
	v_fmamk_f32 v132, v134, 0x3e38aa3b, v251
	v_exp_f32_e32 v132, v132
	v_fmamk_f32 v133, v135, 0x3e38aa3b, v251
	v_exp_f32_e32 v133, v133
	v_fmamk_f32 v134, v136, 0x3e38aa3b, v251
	v_exp_f32_e32 v134, v134
	v_fmamk_f32 v135, v137, 0x3e38aa3b, v251
	v_exp_f32_e32 v135, v135
	v_add_f32_e32 v136, v132, v252
	v_add_f32_e32 v136, v133, v136
	v_add_f32_e32 v136, v134, v136
	v_add_f32_e32 v252, v135, v136
	v_fmamk_f32 v136, v138, 0x3e38aa3b, v251
	v_exp_f32_e32 v136, v136
	v_fmamk_f32 v137, v139, 0x3e38aa3b, v251
	v_exp_f32_e32 v137, v137
	v_fmamk_f32 v138, v140, 0x3e38aa3b, v251
	v_exp_f32_e32 v138, v138
	v_fmamk_f32 v139, v141, 0x3e38aa3b, v251
	v_exp_f32_e32 v139, v139
	v_add_f32_e32 v140, v136, v252
	v_add_f32_e32 v140, v137, v140
	v_add_f32_e32 v140, v138, v140
	v_add_f32_e32 v252, v139, v140
	v_fmamk_f32 v140, v142, 0x3e38aa3b, v251
	v_exp_f32_e32 v140, v140
	v_fmamk_f32 v141, v143, 0x3e38aa3b, v251
	v_exp_f32_e32 v141, v141
	v_fmamk_f32 v142, v160, 0x3e38aa3b, v251
	v_exp_f32_e32 v142, v142
	v_fmamk_f32 v143, v161, 0x3e38aa3b, v251
	v_exp_f32_e32 v143, v143
	v_add_f32_e32 v160, v140, v252
	v_add_f32_e32 v160, v141, v160
	v_add_f32_e32 v160, v142, v160
	v_add_f32_e32 v252, v143, v160
	v_fmamk_f32 v160, v162, 0x3e38aa3b, v251
	v_exp_f32_e32 v160, v160
	v_fmamk_f32 v161, v163, 0x3e38aa3b, v251
	v_exp_f32_e32 v161, v161
	v_fmamk_f32 v162, v164, 0x3e38aa3b, v251
	v_exp_f32_e32 v162, v162
	v_fmamk_f32 v163, v165, 0x3e38aa3b, v251
	v_exp_f32_e32 v163, v163
	v_add_f32_e32 v164, v160, v252
	v_add_f32_e32 v164, v161, v164
	v_add_f32_e32 v164, v162, v164
	v_add_f32_e32 v252, v163, v164
	v_fmamk_f32 v164, v166, 0x3e38aa3b, v251
	v_exp_f32_e32 v164, v164
	v_fmamk_f32 v165, v167, 0x3e38aa3b, v251
	v_exp_f32_e32 v165, v165
	v_fmamk_f32 v166, v168, 0x3e38aa3b, v251
	v_exp_f32_e32 v166, v166
	v_fmamk_f32 v167, v169, 0x3e38aa3b, v251
	v_exp_f32_e32 v167, v167
	v_add_f32_e32 v168, v164, v252
	v_add_f32_e32 v168, v165, v168
	v_add_f32_e32 v168, v166, v168
	v_add_f32_e32 v252, v167, v168
	v_fmamk_f32 v168, v170, 0x3e38aa3b, v251
	v_exp_f32_e32 v168, v168
	v_fmamk_f32 v169, v171, 0x3e38aa3b, v251
	v_exp_f32_e32 v169, v169
	v_fmamk_f32 v170, v172, 0x3e38aa3b, v251
	v_exp_f32_e32 v170, v170
	v_fmamk_f32 v171, v173, 0x3e38aa3b, v251
	v_exp_f32_e32 v171, v171
	v_add_f32_e32 v172, v168, v252
	v_add_f32_e32 v172, v169, v172
	v_add_f32_e32 v172, v170, v172
	v_add_f32_e32 v252, v171, v172
	v_fmamk_f32 v172, v174, 0x3e38aa3b, v251
	v_exp_f32_e32 v172, v172
	v_fmamk_f32 v173, v175, 0x3e38aa3b, v251
	v_exp_f32_e32 v173, v173
	v_fmamk_f32 v174, v198, 0x3e38aa3b, v251
	v_exp_f32_e32 v174, v174
	v_fmac_f32_e32 v251, 0x3e38aa3b, v229
	v_exp_f32_e32 v175, v251
	v_add_f32_e32 v198, v172, v252
	v_add_f32_e32 v198, v173, v198
	v_add_f32_e32 v198, v174, v198
	v_add_f32_e32 v229, v175, v198
	v_exp_f32_e32 v198, v250
	v_mov_b32_e32 v250, v229
	s_nop 1
	v_permlane32_swap_b32_e32 v229, v250
	v_cmp_gt_f32_e32 vcc, v249, v201
	v_add_f32_e32 v250, v229, v250
	s_cmp_lg_u64 vcc, 0
	v_fmac_f32_e32 v250, v200, v198
	s_cselect_b64 s[12:13], -1, 0
	s_cbranch_execnz .LBB0_1783

; #define MFMA32(a, b, c) __builtin_amdgcn_mfma_f32_32x32x16_bf16((a), (b), (c), 0, 0, 0)
; DI void pv_tile(const u16* Vs, const f32x16* s, f32x16* o, int rl, int hh) {
; #pragma unroll
;   for (int kk = 0; kk < 4; ++kk) {
;     const int kb = kk >> 1, i0 = 8 * (kk & 1);
;     bf16x8 pf = pack8(s[kb][i0], s[kb][i0 + 1], s[kb][i0 + 2], s[kb][i0 + 3], s[kb][i0 + 4], s[kb][i0 + 5], s[kb][i0 + 6], s[kb][i0 + 7]);
; #pragma unroll
;     for (int db = 0; db < 2; ++db) {
;       const u16* vp = Vs + (db * 32 + rl) * KVS + kk * 16 + hh * 4;
;       s16x4 lo = *(const s16x4*)vp, hi = *(const s16x4*)(vp + 8);
;       bf16x8 a = __builtin_shufflevector(lo, hi, 0, 1, 2, 3, 4, 5, 6, 7);
;       o[db] = MFMA32(a, pf, o[db]);
;     }
;   }
; }
.LBB0_1787:
	s_nop 0
	v_lshlrev_b32_e32 v116, 1, v246
	v_add3_u32 v120, v202, v247, v116
	s_nop 2
	v_add_u32_e32 v121, 0x2000, v120
	v_add_u32_e32 v120, 0x3000, v120
	ds_read2_b64 v[144:147], v121 offset0:128 offset1:130
	ds_read2_b64 v[148:151], v120 offset0:192 offset1:194
	ds_read2_b64 v[152:155], v121 offset0:132 offset1:134
	ds_read2_b64 v[156:159], v120 offset0:196 offset1:198
	ds_read2_b64 v[116:119], v121 offset0:136 offset1:138
	ds_read2_b64 v[124:127], v120 offset0:200 offset1:202
	v_cvt_pk_bf16_f32 v112, v128, v129
	v_cvt_pk_bf16_f32 v113, v130, v131
	v_cvt_pk_bf16_f32 v114, v132, v133
	v_cvt_pk_bf16_f32 v115, v134, v135
	s_nop 1
	ds_read2_b64 v[128:131], v121 offset0:140 offset1:142
	ds_read2_b64 v[132:135], v120 offset0:204 offset1:206
	s_waitcnt lgkmcnt(7)
	v_mfma_f32_32x32x16_bf16 v[96:111], v[144:147], v[112:115], v[96:111]
	s_waitcnt lgkmcnt(6)
	v_mfma_f32_32x32x16_bf16 v[80:95], v[148:151], v[112:115], v[80:95]
	v_cvt_pk_bf16_f32 v112, v136, v137
	v_cvt_pk_bf16_f32 v113, v138, v139
	v_cvt_pk_bf16_f32 v114, v140, v141
	v_cvt_pk_bf16_f32 v115, v142, v143
	s_nop 1
	s_waitcnt lgkmcnt(5)
	v_mfma_f32_32x32x16_bf16 v[96:111], v[152:155], v[112:115], v[96:111]
	s_waitcnt lgkmcnt(4)
	v_mfma_f32_32x32x16_bf16 v[80:95], v[156:159], v[112:115], v[80:95]
	v_cvt_pk_bf16_f32 v112, v160, v161
	v_cvt_pk_bf16_f32 v113, v162, v163
	v_cvt_pk_bf16_f32 v114, v164, v165
	v_cvt_pk_bf16_f32 v115, v166, v167
	s_nop 1
	s_waitcnt lgkmcnt(3)
	v_mfma_f32_32x32x16_bf16 v[96:111], v[116:119], v[112:115], v[96:111]
	s_waitcnt lgkmcnt(2)
	v_mfma_f32_32x32x16_bf16 v[80:95], v[124:127], v[112:115], v[80:95]
	v_cvt_pk_bf16_f32 v112, v168, v169
	v_cvt_pk_bf16_f32 v113, v170, v171
	v_cvt_pk_bf16_f32 v114, v172, v173
	v_cvt_pk_bf16_f32 v115, v174, v175
	s_nop 1
	s_waitcnt lgkmcnt(1)
	v_mfma_f32_32x32x16_bf16 v[96:111], v[128:131], v[112:115], v[96:111]
	s_waitcnt lgkmcnt(0)
	v_mfma_f32_32x32x16_bf16 v[80:95], v[132:135], v[112:115], v[80:95]
	s_andn2_b64 vcc, exec, s[14:15]
	s_cbranch_vccnz .LBB0_1789
